# E20 + loop-edge rotation in both attention loops: on the barrier path the six loop-control SALU ops run before the s_waitcnt/s_barrier instead of after
# baseline (speedup 1.0000x reference)
; #define A_BOT() do { if (t & 1) { A_WAITBAR(0); } } while (0)
; #define A_ROT() do { sk = (t + 1) & 3; sk2 = t & 3; } while (0)
; template <int TYPE> __device__ __forceinline__ void attn_unit(LAS unsigned char* lds, const AttnUnit& U) {
;     ...
;     int t = 0, sk = 0, sk2 = 3;
;     const int sk1 = 0; (void)sk1;
;     ...
;         A_BOT(); A_ROT();
;     }
.LBB0_684:
	s_andn2_b64 vcc, exec, s[84:85]
	s_cbranch_vccnz .LBB0_673
	s_and_b32 s72, s83, 3
	s_add_i32 s83, s83, 1
	s_and_b32 s77, s86, 3
	s_addk_i32 s87, 0x2000
	s_add_i32 s6, s95, s83
	s_cmp_lg_u32 s6, 1
	s_waitcnt vmcnt(0) lgkmcnt(0)
	s_barrier
	s_cbranch_scc0 .LBB0_687
	s_branch .LBB0_674

; #define A_BOT() do { if (t & 1) { A_WAITBAR(0); } } while (0)
; #define A_ROT() do { sk = (t + 1) & 3; sk2 = t & 3; } while (0)
; template <int TYPE> __device__ __forceinline__ void attn_unit(LAS unsigned char* lds, const AttnUnit& U) {
;     ...
;     int t = 0, sk = 0, sk2 = 3;
;     const int sk1 = 0; (void)sk1;
;     ...
;         A_BOT(); A_ROT();
;     }
.LBB0_756:
	s_andn2_b64 vcc, exec, s[86:87]
	s_cbranch_vccnz .LBB0_745
	s_and_b32 s72, s93, 3
	s_add_i32 s93, s93, 1
	s_and_b32 s77, s85, 3
	s_addk_i32 s84, 0x2000
	s_add_i32 s73, s33, s93
	s_cmp_lg_u32 s73, 1
	s_waitcnt vmcnt(0) lgkmcnt(0)
	s_barrier
	s_cbranch_scc0 .LBB0_759
	s_branch .LBB0_746
